# decode SSD item: conv-history staging loop issues its nine global loads together, one wait instead of three dependent waits per trip
# baseline (speedup 1.0000x reference)
; DI float bf2f(u16 h) { return __uint_as_float(((unsigned)h) << 16); }
; DI float siluf(float x) { return x * __builtin_amdgcn_rcpf(1.f + __expf(-x)); }
; DI void ssd_sample_item(char* shm, const Params& P, int l, int s, int g) {
;     ...
;   for (int u = tid; u < 768; u += NT) {
;     int ch; float* dst;
;     if (u < 512) { ch = g * 512 + u; dst = xs + u; } else if (u < 640) { ch = 1024 + g * 128 + (u - 512); dst = Bs + (u - 512); } else { ch = 1280 + g * 128 + (u - 640); dst = Cs + (u - 640); }
;     const float h0 = hist[ch], h1 = hist[1536 + ch], h2 = hist[2 * 1536 + ch], nw = bf2f(zr[C_CX + ch]);
;     const float a = cb[ch] + cw[ch] * h0 + cw[1536 + ch] * h1 + cw[2 * 1536 + ch] * h2 + cw[3 * 1536 + ch] * nw;
;     *dst = siluf(a);
;     cso[ch] = h1; cso[1536 + ch] = h2; cso[2 * 1536 + ch] = nw;
;   }
.LBB0_145:
	s_or_b64 exec, exec, s[14:15]
	v_ashrrev_i32_e32 v1, 31, v0
	v_lshlrev_b64 v[6:7], 2, v[0:1]
	v_readlane_b32 s2, v255, 20
	v_readlane_b32 s3, v255, 21
	s_waitcnt vmcnt(0)
	v_lshl_add_u64 v[8:9], s[8:9], 0, v[6:7]
	v_lshl_add_u64 v[160:161], v[0:1], 1, s[4:5]
	v_lshl_add_u64 v[162:163], s[66:67], 0, v[6:7]
	v_lshl_add_u64 v[164:165], s[2:3], 0, v[6:7]
	v_add_co_u32_e32 v166, vcc, 0x1000, v8
	s_nop 1
	v_addc_co_u32_e32 v167, vcc, 0, v9, vcc
	v_add_co_u32_e32 v168, vcc, 0x3000, v8
	s_nop 1
	v_addc_co_u32_e32 v169, vcc, 0, v9, vcc
	v_add_co_u32_e32 v160, vcc, 0x2000, v160
	s_nop 1
	v_addc_co_u32_e32 v161, vcc, 0, v161, vcc
	v_add_co_u32_e32 v170, vcc, s60, v164
	s_nop 1
	v_addc_co_u32_e32 v171, vcc, 0, v165, vcc
	v_add_co_u32_e32 v172, vcc, s61, v164
	s_nop 1
	v_addc_co_u32_e32 v173, vcc, 0, v165, vcc
	v_add_co_u32_e32 v174, vcc, s57, v164
	s_nop 1
	v_addc_co_u32_e32 v175, vcc, 0, v165, vcc
	global_load_dword v10, v[8:9], off
	global_load_dword v11, v[166:167], off offset:2048
	global_load_dword v176, v[168:169], off
	global_load_ushort v177, v[160:161], off offset:3072
	global_load_dword v16, v[162:163], off
	global_load_dword v12, v[164:165], off
	global_load_dword v13, v[170:171], off offset:2048
	global_load_dword v178, v[172:173], off
	global_load_dword v179, v[174:175], off offset:2048
	s_waitcnt vmcnt(0)
	v_lshlrev_b32_e32 v177, 16, v177
	v_pk_mul_f32 v[12:13], v[10:11], v[12:13]
	s_nop 0
	v_add_f32_e32 v10, v16, v12
	v_add_f32_e32 v10, v10, v13
	v_pk_mul_f32 v[0:1], v[178:179], v[176:177]
	s_nop 0
	v_add_f32_e32 v0, v10, v0
	v_add_f32_e32 v0, v0, v1
	v_mul_f32_e32 v1, 0xbfb8aa3b, v0
	v_exp_f32_e32 v1, v1
	s_nop 0
	v_add_f32_e32 v1, 1.0, v1
	v_rcp_f32_e32 v1, v1
	s_nop 0
	v_mul_f32_e32 v0, v0, v1
	ds_write_b32 v4, v0
	v_lshl_add_u64 v[0:1], s[10:11], 0, v[6:7]
	v_add_co_u32_e32 v6, vcc, 0x1000, v0
	global_store_dword v[0:1], v11, off
	s_nop 0
	v_addc_co_u32_e32 v7, vcc, 0, v1, vcc
	v_add_co_u32_e32 v0, vcc, 0x3000, v0
	v_add_u32_e32 v4, 0x800, v4
	s_nop 0
	v_addc_co_u32_e32 v1, vcc, 0, v1, vcc
	global_store_dword v[0:1], v177, off
	v_add_u32_e32 v0, 0x200, v5
	v_cmp_lt_i32_e32 vcc, s64, v5
	s_or_b64 s[12:13], vcc, s[12:13]
	v_mov_b32_e32 v5, v0
	global_store_dword v[6:7], v176, off offset:2048
	s_andn2_b64 exec, exec, s[12:13]
	s_cbranch_execz .LBB0_154
